# P5 w2 staging loop unrolled: eight loads in flight behind counted waits instead of eight load-wait-store rungs
# baseline (speedup 1.0000x reference)
; #define LAS __attribute__((address_space(3)))
; __global__ void __launch_bounds__(NTHR, 2) hybrid_fwd(Args args) {
;     ...
;             {
;                 LAS float* w2k = (LAS float*)lds;
;                 LAS float* w2v = (LAS float*)(lds + 32768);
;                 LAS float* hs = (LAS float*)(lds + 65536) + wave * 256;
;                 __syncthreads();
;                 for (int i = tid; i < 2048; i += NTHR) { ((LAS f32x4*)w2k)[i] = ((const f32x4*)w_ck2)[i]; ((LAS f32x4*)w2v)[i] = ((const f32x4*)w_cv2)[i]; }
;                 __syncthreads();
.LBB0_891:
	global_load_dwordx4 v[8:11], v[2:3], off
	global_load_dwordx4 v[12:15], v[4:5], off
	v_lshl_add_u64 v[2:3], v[2:3], 0, s[14:15]
	v_lshl_add_u64 v[4:5], v[4:5], 0, s[14:15]
	global_load_dwordx4 v[16:19], v[2:3], off
	global_load_dwordx4 v[20:23], v[4:5], off
	v_lshl_add_u64 v[2:3], v[2:3], 0, s[14:15]
	v_lshl_add_u64 v[4:5], v[4:5], 0, s[14:15]
	global_load_dwordx4 v[24:27], v[2:3], off
	global_load_dwordx4 v[28:31], v[4:5], off
	v_lshl_add_u64 v[2:3], v[2:3], 0, s[14:15]
	v_lshl_add_u64 v[4:5], v[4:5], 0, s[14:15]
	global_load_dwordx4 v[32:35], v[2:3], off
	global_load_dwordx4 v[36:39], v[4:5], off
	s_waitcnt vmcnt(6)
	ds_write_b128 v6, v[8:11]
	ds_write_b128 v6, v[12:15] offset:32768
	s_waitcnt vmcnt(4)
	ds_write_b128 v6, v[16:19] offset:8192
	ds_write_b128 v6, v[20:23] offset:40960
	s_waitcnt vmcnt(2)
	ds_write_b128 v6, v[24:27] offset:16384
	ds_write_b128 v6, v[28:31] offset:49152
	s_waitcnt vmcnt(0)
	ds_write_b128 v6, v[32:35] offset:24576
	ds_write_b128 v6, v[36:39] offset:57344
